# opt16
# speedup vs baseline: 1.0153x; 1.0153x over previous
; __device__ __forceinline__ float sigm(float x) { return __builtin_amdgcn_rcpf(1.f + __expf(-x)); }
; #define WAIT_V(n) asm volatile("s_waitcnt vmcnt(" #n ")" ::: "memory")
; #define BAR __builtin_amdgcn_s_barrier()
; template <bool PEEL = false>
; __device__ __forceinline__ void gemm_tile(f32x4 (&acc)[2][2][4][2], const u16* __restrict__ A, int lda,
;                                           const u16* __restrict__ B, int K) {
;     ...
;   STAGE_B(SB(0, 0), 0, 0); STAGE_A(SA(0, 0), 0, 0);
;   STAGE_B(SB(0, 1), 1, 0); STAGE_A(SA(0, 1), 1, 0);
;   if (wr == 1) BAR;
;   WAIT_V(4); BAR;
;   STAGE_B(SB(1, 0), 0, 1); STAGE_A(SA(1, 0), 0, 1); STAGE_B(SB(1, 1), 1, 1);
; __device__ __forceinline__ void gemm_glu_merge(u16* __restrict__ proj, const u16* __restrict__ Wt) {
;     ...
;         for (int j = 0; j < 4; ++j) {
;           const int row = ai * 128 + wr * 64 + m * 16 + fq * 4 + j;
;           u16* pr = proj + (size_t)row * 4096 + nt * 128 + wc * 32 + fr * 2;
;           const float s0 = acc[ai][0][m][0][j] * sigm(acc[ai][0][m][1][j]);
;           const float s1 = acc[ai][1][m][0][j] * sigm(acc[ai][1][m][1][j]);
;           const unsigned at = *(const unsigned*)pr, ga = *(const unsigned*)(pr + 2048), gs = *(const unsigned*)(pr + 3072);
;           const float m0 = sigm(__uint_as_float(ga << 16)) * __uint_as_float(at << 16) + sigm(__uint_as_float(gs << 16)) * s0;
;           const float m1 = sigm(__uint_as_float(ga & 0xffff0000u)) * __uint_as_float(at & 0xffff0000u) +
;                            sigm(__uint_as_float(gs & 0xffff0000u)) * s1;
;           __builtin_nontemporal_store(pack2(m0, m1), (unsigned*)pr);
.LBB0_360:
	s_or_b64 exec, exec, s[2:3]
	s_mov_b32 s30, 0xbfb8aa3b
	s_mov_b32 s31, 0xbfb8aa3b
	s_mov_b32 s34, 1.0
	s_mov_b32 s35, 1.0
	v_lshlrev_b32_e32 v128, 6, v132
	v_lshl_add_u32 v128, v135, 2, v128
	v_lshlrev_b32_e32 v128, 13, v128
	s_lshl_b32 s2, s12, 8
	v_lshl_add_u32 v129, v133, 6, s2
	v_lshl_add_u32 v129, v134, 2, v129
	v_add_u32_e32 v137, v128, v129
	s_add_u32 s2, s64, 0x1000
	s_addc_u32 s3, s65, 0
	global_load_dword v138, v137, s[2:3] offset:-4096
	global_load_dword v140, v137, s[2:3]
	global_load_dword v142, v137, s[2:3] offset:2048
	s_add_u32 s2, s64, 0x3000
	s_addc_u32 s3, s65, 0
	global_load_dword v139, v137, s[2:3] offset:-4096
	global_load_dword v141, v137, s[2:3]
	global_load_dword v143, v137, s[2:3] offset:2048
	s_add_u32 s2, s64, 0x5000
	s_addc_u32 s3, s65, 0
	global_load_dword v144, v137, s[2:3] offset:-4096
	global_load_dword v146, v137, s[2:3]
	global_load_dword v148, v137, s[2:3] offset:2048
	s_add_u32 s2, s64, 0x7000
	s_addc_u32 s3, s65, 0
	global_load_dword v145, v137, s[2:3] offset:-4096
	global_load_dword v147, v137, s[2:3]
	global_load_dword v149, v137, s[2:3] offset:2048
	s_add_u32 s2, s64, 0x21000
	s_addc_u32 s3, s65, 0
	global_load_dword v150, v137, s[2:3] offset:-4096
	global_load_dword v152, v137, s[2:3]
	global_load_dword v154, v137, s[2:3] offset:2048
	s_add_u32 s2, s64, 0x23000
	s_addc_u32 s3, s65, 0
	global_load_dword v151, v137, s[2:3] offset:-4096
	global_load_dword v153, v137, s[2:3]
	global_load_dword v155, v137, s[2:3] offset:2048
	s_add_u32 s2, s64, 0x25000
	s_addc_u32 s3, s65, 0
	global_load_dword v156, v137, s[2:3] offset:-4096
	global_load_dword v158, v137, s[2:3]
	global_load_dword v160, v137, s[2:3] offset:2048
	s_add_u32 s2, s64, 0x27000
	s_addc_u32 s3, s65, 0
	global_load_dword v157, v137, s[2:3] offset:-4096
	global_load_dword v159, v137, s[2:3]
	global_load_dword v161, v137, s[2:3] offset:2048
	s_add_u32 s2, s64, 0x41000
	s_addc_u32 s3, s65, 0
	global_load_dword v162, v137, s[2:3] offset:-4096
	global_load_dword v164, v137, s[2:3]
	global_load_dword v166, v137, s[2:3] offset:2048
	s_add_u32 s2, s64, 0x43000
	s_addc_u32 s3, s65, 0
	global_load_dword v163, v137, s[2:3] offset:-4096
	global_load_dword v165, v137, s[2:3]
	global_load_dword v167, v137, s[2:3] offset:2048
	s_cmp_eq_u32 s12, 7
	s_cbranch_scc1 .Lpf4_skip
	v_and_b32_e32 v240, 63, v254
	v_lshlrev_b32_e32 v235, 4, v240
	v_and_b32_e32 v236, 32, v240
	v_xor_b32_e32 v235, v235, v236
	v_lshrrev_b32_e32 v237, 6, v235
	v_and_b32_e32 v235, 63, v235
	v_lshl_add_u32 v235, v237, 13, v235
	v_lshrrev_b32_e32 v237, 6, v254
	v_and_b32_e32 v238, 1, v237
	v_lshl_add_u32 v235, v238, 6, v235
	v_lshrrev_b32_e32 v237, 1, v237
	v_lshl_add_u32 v240, v237, 17, v235
	v_and_b32_e32 v242, 63, v254
	v_lshlrev_b32_e32 v235, 4, v242
	v_and_b32_e32 v236, 32, v242
	v_xor_b32_e32 v235, v235, v236
	v_lshrrev_b32_e32 v237, 6, v235
	v_and_b32_e32 v235, 63, v235
	v_lshl_add_u32 v235, v237, 10, v235
	v_lshrrev_b32_e32 v237, 6, v254
	v_and_b32_e32 v238, 1, v237
	v_lshl_add_u32 v235, v238, 6, v235
	v_lshrrev_b32_e32 v237, 1, v237
	v_lshl_add_u32 v242, v237, 14, v235
	s_add_i32 s2, s12, 1
	s_lshl_b32 s2, s2, 18
	s_add_u32 s8, s0, s2
	s_addc_u32 s9, s1, 0
	s_and_b32 s9, s9, 0xffff
	s_mov_b32 s10, s6
	s_mov_b32 s11, s7
	s_mov_b32 m0, s45
	s_nop 0
	buffer_load_dwordx4 v242, s[8:11], 0 offen lds
	s_mov_b32 m0, s46
	s_nop 0
	buffer_load_dwordx4 v242, s[8:11], s14 offen lds
	s_mov_b32 m0, s44
	s_nop 0
	buffer_load_dwordx4 v240, s[4:7], 0 offen lds
	s_mov_b32 m0, s47
	s_nop 0
	buffer_load_dwordx4 v240, s[4:7], s15 offen lds
	s_mov_b32 m0, s48
	s_nop 0
	buffer_load_dwordx4 v242, s[8:11], s7 offen lds
	s_mov_b32 m0, s49
	s_nop 0
	buffer_load_dwordx4 v242, s[8:11], s16 offen lds
	s_mov_b32 m0, s52
	s_nop 0
	buffer_load_dwordx4 v240, s[4:7], s17 offen lds
	s_mov_b32 m0, s53
	s_nop 0
	buffer_load_dwordx4 v240, s[4:7], s18 offen lds
	s_add_i32 m0, s44, 0x18000
	s_nop 0
	buffer_load_dwordx4 v242, s[8:11], s19 offen lds
	s_add_i32 m0, s44, 0x1a000
	s_nop 0
	buffer_load_dwordx4 v242, s[8:11], s20 offen lds
	s_mov_b32 m0, s66
	s_nop 0
	buffer_load_dwordx4 v240, s[4:7], s19 offen lds
	s_mov_b32 m0, s67
	s_nop 0
	buffer_load_dwordx4 v240, s[4:7], s21 offen lds
	s_mov_b32 m0, s78
	s_nop 0
	buffer_load_dwordx4 v242, s[8:11], s22 offen lds
	s_mov_b32 m0, s79
	s_nop 0
	buffer_load_dwordx4 v242, s[8:11], s23 offen lds
.Lpf4_skip:
	s_add_u32 s2, s64, 0x45000
	s_addc_u32 s3, s65, 0
	global_load_dword v168, v137, s[2:3] offset:-4096
	global_load_dword v170, v137, s[2:3]
	global_load_dword v172, v137, s[2:3] offset:2048
	s_add_u32 s2, s64, 0x47000
	s_addc_u32 s3, s65, 0
	global_load_dword v169, v137, s[2:3] offset:-4096
	global_load_dword v171, v137, s[2:3]
	global_load_dword v173, v137, s[2:3] offset:2048
	v_pk_mul_f32 v[120:121], v[120:121], s[30:31]
	v_pk_mul_f32 v[124:125], v[124:125], s[30:31]
	v_pk_mul_f32 v[122:123], v[122:123], s[30:31]
	v_pk_mul_f32 v[126:127], v[126:127], s[30:31]
	v_exp_f32_e32 v120, v120
	v_exp_f32_e32 v121, v121
	v_exp_f32_e32 v124, v124
	v_exp_f32_e32 v125, v125
	v_exp_f32_e32 v122, v122
	v_exp_f32_e32 v123, v123
	v_exp_f32_e32 v126, v126
	v_exp_f32_e32 v127, v127
	v_pk_add_f32 v[120:121], v[120:121], s[34:35]
	v_pk_add_f32 v[124:125], v[124:125], s[34:35]
	v_pk_add_f32 v[122:123], v[122:123], s[34:35]
	v_pk_add_f32 v[126:127], v[126:127], s[34:35]
	v_rcp_f32_e32 v120, v120
	v_rcp_f32_e32 v121, v121
	v_rcp_f32_e32 v124, v124
	v_rcp_f32_e32 v125, v125
	v_rcp_f32_e32 v122, v122
	v_rcp_f32_e32 v123, v123
	v_rcp_f32_e32 v126, v126
	v_rcp_f32_e32 v127, v127
	v_pk_mul_f32 v[112:113], v[112:113], v[120:121]
	v_pk_mul_f32 v[116:117], v[116:117], v[124:125]
	v_pk_mul_f32 v[114:115], v[114:115], v[122:123]
	v_pk_mul_f32 v[118:119], v[118:119], v[126:127]
	s_cmp_eq_u32 s12, 7
	s_cbranch_scc1 .Lgw_last0
	s_waitcnt vmcnt(44)
	s_branch .Lgw_join0
; __device__ __forceinline__ float sigm(float x) { return __builtin_amdgcn_rcpf(1.f + __expf(-x)); }
; __device__ __forceinline__ void gemm_glu_merge(u16* __restrict__ proj, const u16* __restrict__ Wt) {
;     ...
;           u16* pr = proj + (size_t)row * 4096 + nt * 128 + wc * 32 + fr * 2;
;           const float s0 = acc[ai][0][m][0][j] * sigm(acc[ai][0][m][1][j]);
;           const float s1 = acc[ai][1][m][0][j] * sigm(acc[ai][1][m][1][j]);
;           const unsigned at = *(const unsigned*)pr, ga = *(const unsigned*)(pr + 2048), gs = *(const unsigned*)(pr + 3072);
;           const float m0 = sigm(__uint_as_float(ga << 16)) * __uint_as_float(at << 16) + sigm(__uint_as_float(gs << 16)) * s0;
;           const float m1 = sigm(__uint_as_float(ga & 0xffff0000u)) * __uint_as_float(at & 0xffff0000u) +
;                            sigm(__uint_as_float(gs & 0xffff0000u)) * s1;
;           __builtin_nontemporal_store(pack2(m0, m1), (unsigned*)pr);
.Lgw_last0:
	s_waitcnt vmcnt(30)
.Lgw_join0:
	v_lshlrev_b32_e32 v238, 16, v138
	v_lshlrev_b32_e32 v239, 16, v139
	v_lshlrev_b32_e32 v240, 16, v140
	v_lshlrev_b32_e32 v241, 16, v141
	v_lshlrev_b32_e32 v242, 16, v142
	v_lshlrev_b32_e32 v243, 16, v143
	v_and_b32_e32 v138, 0xffff0000, v138
	v_and_b32_e32 v139, 0xffff0000, v139
	v_and_b32_e32 v140, 0xffff0000, v140
	v_and_b32_e32 v141, 0xffff0000, v141
	v_and_b32_e32 v142, 0xffff0000, v142
	v_and_b32_e32 v143, 0xffff0000, v143
	v_pk_mul_f32 v[240:241], v[240:241], s[30:31]
	v_pk_mul_f32 v[140:141], v[140:141], s[30:31]
	v_pk_mul_f32 v[242:243], v[242:243], s[30:31]
	v_pk_mul_f32 v[142:143], v[142:143], s[30:31]
	v_exp_f32_e32 v240, v240
	v_exp_f32_e32 v241, v241
	v_exp_f32_e32 v140, v140
	v_exp_f32_e32 v141, v141
	v_exp_f32_e32 v242, v242
	v_exp_f32_e32 v243, v243
	v_exp_f32_e32 v142, v142
	v_exp_f32_e32 v143, v143
	v_pk_add_f32 v[240:241], v[240:241], s[34:35]
	v_pk_add_f32 v[140:141], v[140:141], s[34:35]
	v_pk_add_f32 v[242:243], v[242:243], s[34:35]
	v_pk_add_f32 v[142:143], v[142:143], s[34:35]
	v_rcp_f32_e32 v240, v240
	v_rcp_f32_e32 v241, v241
	v_rcp_f32_e32 v140, v140
	v_rcp_f32_e32 v141, v141
	v_rcp_f32_e32 v242, v242
	v_rcp_f32_e32 v243, v243
	v_rcp_f32_e32 v142, v142
	v_rcp_f32_e32 v143, v143
	v_pk_mul_f32 v[238:239], v[240:241], v[238:239]
	v_pk_mul_f32 v[138:139], v[140:141], v[138:139]
	v_pk_fma_f32 v[238:239], v[242:243], v[112:113], v[238:239]
	v_pk_fma_f32 v[138:139], v[142:143], v[116:117], v[138:139]
	v_cvt_pk_bf16_f32 v240, v238, v138
	v_cvt_pk_bf16_f32 v241, v239, v139
	s_add_u32 s2, s64, 0x1000
	s_addc_u32 s3, s65, 0
	global_store_dword v137, v240, s[2:3] offset:-4096 nt
	s_add_u32 s2, s64, 0x3000
	s_addc_u32 s3, s65, 0
	global_store_dword v137, v241, s[2:3] offset:-4096 nt
	s_add_u32 s2, s64, 0x61000
	s_addc_u32 s3, s65, 0
	global_load_dword v174, v137, s[2:3] offset:-4096
	global_load_dword v176, v137, s[2:3]
	global_load_dword v178, v137, s[2:3] offset:2048
	s_add_u32 s2, s64, 0x63000
	s_addc_u32 s3, s65, 0
	global_load_dword v175, v137, s[2:3] offset:-4096
	global_load_dword v177, v137, s[2:3]
	global_load_dword v179, v137, s[2:3] offset:2048
	s_cmp_eq_u32 s12, 7
	s_cbranch_scc1 .Lgw_last1
	s_waitcnt vmcnt(46)
	s_branch .Lgw_join1
.Lgw_last1:
	s_waitcnt vmcnt(32)
.Lgw_join1:
	v_lshlrev_b32_e32 v248, 16, v144
	v_lshlrev_b32_e32 v249, 16, v145
	v_lshlrev_b32_e32 v250, 16, v146
	v_lshlrev_b32_e32 v251, 16, v147
	v_lshlrev_b32_e32 v252, 16, v148
	v_lshlrev_b32_e32 v253, 16, v149
	v_and_b32_e32 v144, 0xffff0000, v144
	v_and_b32_e32 v145, 0xffff0000, v145
	v_and_b32_e32 v146, 0xffff0000, v146
	v_and_b32_e32 v147, 0xffff0000, v147
	v_and_b32_e32 v148, 0xffff0000, v148
	v_and_b32_e32 v149, 0xffff0000, v149
	v_pk_mul_f32 v[250:251], v[250:251], s[30:31]
	v_pk_mul_f32 v[146:147], v[146:147], s[30:31]
	v_pk_mul_f32 v[252:253], v[252:253], s[30:31]
	v_pk_mul_f32 v[148:149], v[148:149], s[30:31]
	v_exp_f32_e32 v250, v250
	v_exp_f32_e32 v251, v251
	v_exp_f32_e32 v146, v146
	v_exp_f32_e32 v147, v147
	v_exp_f32_e32 v252, v252
	v_exp_f32_e32 v253, v253
	v_exp_f32_e32 v148, v148
	v_exp_f32_e32 v149, v149
	v_pk_add_f32 v[250:251], v[250:251], s[34:35]
	v_pk_add_f32 v[146:147], v[146:147], s[34:35]
	v_pk_add_f32 v[252:253], v[252:253], s[34:35]
	v_pk_add_f32 v[148:149], v[148:149], s[34:35]
	v_rcp_f32_e32 v250, v250
	v_rcp_f32_e32 v251, v251
	v_rcp_f32_e32 v146, v146
	v_rcp_f32_e32 v147, v147
	v_rcp_f32_e32 v252, v252
	v_rcp_f32_e32 v253, v253
	v_rcp_f32_e32 v148, v148
	v_rcp_f32_e32 v149, v149
	v_pk_mul_f32 v[248:249], v[250:251], v[248:249]
	v_pk_mul_f32 v[144:145], v[146:147], v[144:145]
	v_pk_fma_f32 v[248:249], v[252:253], v[114:115], v[248:249]
	v_pk_fma_f32 v[144:145], v[148:149], v[118:119], v[144:145]
	v_cvt_pk_bf16_f32 v250, v248, v144
	v_cvt_pk_bf16_f32 v251, v249, v145
	s_add_u32 s2, s64, 0x5000
	s_addc_u32 s3, s65, 0
	global_store_dword v137, v250, s[2:3] offset:-4096 nt
	s_add_u32 s2, s64, 0x7000
	s_addc_u32 s3, s65, 0
	global_store_dword v137, v251, s[2:3] offset:-4096 nt
	s_add_u32 s2, s64, 0x65000
	s_addc_u32 s3, s65, 0
	global_load_dword v180, v137, s[2:3] offset:-4096
	global_load_dword v182, v137, s[2:3]
	global_load_dword v184, v137, s[2:3] offset:2048
	s_add_u32 s2, s64, 0x67000
	s_addc_u32 s3, s65, 0
	global_load_dword v181, v137, s[2:3] offset:-4096
	global_load_dword v183, v137, s[2:3]
	global_load_dword v185, v137, s[2:3] offset:2048
	v_pk_mul_f32 v[104:105], v[104:105], s[30:31]
	v_pk_mul_f32 v[108:109], v[108:109], s[30:31]
	v_pk_mul_f32 v[106:107], v[106:107], s[30:31]
	v_pk_mul_f32 v[110:111], v[110:111], s[30:31]
	v_exp_f32_e32 v104, v104
	v_exp_f32_e32 v105, v105
	v_exp_f32_e32 v108, v108
	v_exp_f32_e32 v109, v109
	v_exp_f32_e32 v106, v106
	v_exp_f32_e32 v107, v107
	v_exp_f32_e32 v110, v110
	v_exp_f32_e32 v111, v111
	v_pk_add_f32 v[104:105], v[104:105], s[34:35]
	v_pk_add_f32 v[108:109], v[108:109], s[34:35]
	v_pk_add_f32 v[106:107], v[106:107], s[34:35]
	v_pk_add_f32 v[110:111], v[110:111], s[34:35]
	v_rcp_f32_e32 v104, v104
	v_rcp_f32_e32 v105, v105
	v_rcp_f32_e32 v108, v108
	v_rcp_f32_e32 v109, v109
	v_rcp_f32_e32 v106, v106
	v_rcp_f32_e32 v107, v107
	v_rcp_f32_e32 v110, v110
	v_rcp_f32_e32 v111, v111
	v_pk_mul_f32 v[96:97], v[96:97], v[104:105]
	v_pk_mul_f32 v[100:101], v[100:101], v[108:109]
	v_pk_mul_f32 v[98:99], v[98:99], v[106:107]
	v_pk_mul_f32 v[102:103], v[102:103], v[110:111]
	s_cmp_eq_u32 s12, 7
	s_cbranch_scc1 .Lgw_last2
	s_waitcnt vmcnt(48)
	s_branch .Lgw_join2
.Lgw_last2:
	s_waitcnt vmcnt(34)
; __device__ __forceinline__ float sigm(float x) { return __builtin_amdgcn_rcpf(1.f + __expf(-x)); }
; __device__ __forceinline__ void gemm_glu_merge(u16* __restrict__ proj, const u16* __restrict__ Wt) {
;     ...
;           u16* pr = proj + (size_t)row * 4096 + nt * 128 + wc * 32 + fr * 2;
;           const float s0 = acc[ai][0][m][0][j] * sigm(acc[ai][0][m][1][j]);
;           const float s1 = acc[ai][1][m][0][j] * sigm(acc[ai][1][m][1][j]);
;           const unsigned at = *(const unsigned*)pr, ga = *(const unsigned*)(pr + 2048), gs = *(const unsigned*)(pr + 3072);
;           const float m0 = sigm(__uint_as_float(ga << 16)) * __uint_as_float(at << 16) + sigm(__uint_as_float(gs << 16)) * s0;
;           const float m1 = sigm(__uint_as_float(ga & 0xffff0000u)) * __uint_as_float(at & 0xffff0000u) +
;                            sigm(__uint_as_float(gs & 0xffff0000u)) * s1;
;           __builtin_nontemporal_store(pack2(m0, m1), (unsigned*)pr);
.Lgw_join2:
	v_lshlrev_b32_e32 v238, 16, v150
	v_lshlrev_b32_e32 v239, 16, v151
	v_lshlrev_b32_e32 v240, 16, v152
	v_lshlrev_b32_e32 v241, 16, v153
	v_lshlrev_b32_e32 v242, 16, v154
	v_lshlrev_b32_e32 v243, 16, v155
	v_and_b32_e32 v150, 0xffff0000, v150
	v_and_b32_e32 v151, 0xffff0000, v151
	v_and_b32_e32 v152, 0xffff0000, v152
	v_and_b32_e32 v153, 0xffff0000, v153
	v_and_b32_e32 v154, 0xffff0000, v154
	v_and_b32_e32 v155, 0xffff0000, v155
	v_pk_mul_f32 v[240:241], v[240:241], s[30:31]
	v_pk_mul_f32 v[152:153], v[152:153], s[30:31]
	v_pk_mul_f32 v[242:243], v[242:243], s[30:31]
	v_pk_mul_f32 v[154:155], v[154:155], s[30:31]
	v_exp_f32_e32 v240, v240
	v_exp_f32_e32 v241, v241
	v_exp_f32_e32 v152, v152
	v_exp_f32_e32 v153, v153
	v_exp_f32_e32 v242, v242
	v_exp_f32_e32 v243, v243
	v_exp_f32_e32 v154, v154
	v_exp_f32_e32 v155, v155
	v_pk_add_f32 v[240:241], v[240:241], s[34:35]
	v_pk_add_f32 v[152:153], v[152:153], s[34:35]
	v_pk_add_f32 v[242:243], v[242:243], s[34:35]
	v_pk_add_f32 v[154:155], v[154:155], s[34:35]
	v_rcp_f32_e32 v240, v240
	v_rcp_f32_e32 v241, v241
	v_rcp_f32_e32 v152, v152
	v_rcp_f32_e32 v153, v153
	v_rcp_f32_e32 v242, v242
	v_rcp_f32_e32 v243, v243
	v_rcp_f32_e32 v154, v154
	v_rcp_f32_e32 v155, v155
	v_pk_mul_f32 v[238:239], v[240:241], v[238:239]
	v_pk_mul_f32 v[150:151], v[152:153], v[150:151]
	v_pk_fma_f32 v[238:239], v[242:243], v[96:97], v[238:239]
	v_pk_fma_f32 v[150:151], v[154:155], v[100:101], v[150:151]
	v_cvt_pk_bf16_f32 v240, v238, v150
	v_cvt_pk_bf16_f32 v241, v239, v151
	s_add_u32 s2, s64, 0x21000
	s_addc_u32 s3, s65, 0
	global_store_dword v137, v240, s[2:3] offset:-4096 nt
	s_add_u32 s2, s64, 0x23000
	s_addc_u32 s3, s65, 0
	global_store_dword v137, v241, s[2:3] offset:-4096 nt
	s_add_u32 s2, s64, 0x101000
	s_addc_u32 s3, s65, 0
	global_load_dword v186, v137, s[2:3] offset:-4096
	global_load_dword v188, v137, s[2:3]
	global_load_dword v190, v137, s[2:3] offset:2048
	s_add_u32 s2, s64, 0x103000
	s_addc_u32 s3, s65, 0
	global_load_dword v187, v137, s[2:3] offset:-4096
	global_load_dword v189, v137, s[2:3]
	global_load_dword v191, v137, s[2:3] offset:2048
	s_cmp_eq_u32 s12, 7
	s_cbranch_scc1 .Lgw_last3
	s_waitcnt vmcnt(50)
	s_branch .Lgw_join3
.Lgw_last3:
	s_waitcnt vmcnt(36)
.Lgw_join3:
	v_lshlrev_b32_e32 v248, 16, v156
	v_lshlrev_b32_e32 v249, 16, v157
	v_lshlrev_b32_e32 v250, 16, v158
	v_lshlrev_b32_e32 v251, 16, v159
	v_lshlrev_b32_e32 v252, 16, v160
	v_lshlrev_b32_e32 v253, 16, v161
	v_and_b32_e32 v156, 0xffff0000, v156
	v_and_b32_e32 v157, 0xffff0000, v157
	v_and_b32_e32 v158, 0xffff0000, v158
	v_and_b32_e32 v159, 0xffff0000, v159
	v_and_b32_e32 v160, 0xffff0000, v160
	v_and_b32_e32 v161, 0xffff0000, v161
	v_pk_mul_f32 v[250:251], v[250:251], s[30:31]
	v_pk_mul_f32 v[158:159], v[158:159], s[30:31]
	v_pk_mul_f32 v[252:253], v[252:253], s[30:31]
	v_pk_mul_f32 v[160:161], v[160:161], s[30:31]
	v_exp_f32_e32 v250, v250
	v_exp_f32_e32 v251, v251
	v_exp_f32_e32 v158, v158
	v_exp_f32_e32 v159, v159
	v_exp_f32_e32 v252, v252
	v_exp_f32_e32 v253, v253
	v_exp_f32_e32 v160, v160
	v_exp_f32_e32 v161, v161
	v_pk_add_f32 v[250:251], v[250:251], s[34:35]
	v_pk_add_f32 v[158:159], v[158:159], s[34:35]
	v_pk_add_f32 v[252:253], v[252:253], s[34:35]
	v_pk_add_f32 v[160:161], v[160:161], s[34:35]
	v_rcp_f32_e32 v250, v250
	v_rcp_f32_e32 v251, v251
	v_rcp_f32_e32 v158, v158
	v_rcp_f32_e32 v159, v159
	v_rcp_f32_e32 v252, v252
	v_rcp_f32_e32 v253, v253
	v_rcp_f32_e32 v160, v160
	v_rcp_f32_e32 v161, v161
	v_pk_mul_f32 v[248:249], v[250:251], v[248:249]
	v_pk_mul_f32 v[156:157], v[158:159], v[156:157]
	v_pk_fma_f32 v[248:249], v[252:253], v[98:99], v[248:249]
	v_pk_fma_f32 v[156:157], v[160:161], v[102:103], v[156:157]
	v_cvt_pk_bf16_f32 v250, v248, v156
	v_cvt_pk_bf16_f32 v251, v249, v157
	s_add_u32 s2, s64, 0x25000
	s_addc_u32 s3, s65, 0
	global_store_dword v137, v250, s[2:3] offset:-4096 nt
	s_add_u32 s2, s64, 0x27000
	s_addc_u32 s3, s65, 0
	global_store_dword v137, v251, s[2:3] offset:-4096 nt
	s_add_u32 s2, s64, 0x105000
	s_addc_u32 s3, s65, 0
	global_load_dword v192, v137, s[2:3] offset:-4096
	global_load_dword v194, v137, s[2:3]
	global_load_dword v196, v137, s[2:3] offset:2048
	s_add_u32 s2, s64, 0x107000
	s_addc_u32 s3, s65, 0
	global_load_dword v193, v137, s[2:3] offset:-4096
	global_load_dword v195, v137, s[2:3]
	global_load_dword v197, v137, s[2:3] offset:2048
	v_pk_mul_f32 v[88:89], v[88:89], s[30:31]
	v_pk_mul_f32 v[92:93], v[92:93], s[30:31]
	v_pk_mul_f32 v[90:91], v[90:91], s[30:31]
	v_pk_mul_f32 v[94:95], v[94:95], s[30:31]
	v_exp_f32_e32 v88, v88
	v_exp_f32_e32 v89, v89
	v_exp_f32_e32 v92, v92
	v_exp_f32_e32 v93, v93
	v_exp_f32_e32 v90, v90
	v_exp_f32_e32 v91, v91
	v_exp_f32_e32 v94, v94
	v_exp_f32_e32 v95, v95
	v_pk_add_f32 v[88:89], v[88:89], s[34:35]
	v_pk_add_f32 v[92:93], v[92:93], s[34:35]
	v_pk_add_f32 v[90:91], v[90:91], s[34:35]
	v_pk_add_f32 v[94:95], v[94:95], s[34:35]
	v_rcp_f32_e32 v88, v88
	v_rcp_f32_e32 v89, v89
	v_rcp_f32_e32 v92, v92
	v_rcp_f32_e32 v93, v93
	v_rcp_f32_e32 v90, v90
	v_rcp_f32_e32 v91, v91
	v_rcp_f32_e32 v94, v94
	v_rcp_f32_e32 v95, v95
	v_pk_mul_f32 v[80:81], v[80:81], v[88:89]
	v_pk_mul_f32 v[84:85], v[84:85], v[92:93]
	v_pk_mul_f32 v[82:83], v[82:83], v[90:91]
	v_pk_mul_f32 v[86:87], v[86:87], v[94:95]
	s_cmp_eq_u32 s12, 7
	s_cbranch_scc1 .Lgw_last4
	s_waitcnt vmcnt(52)
	s_branch .Lgw_join4
.Lgw_last4:
	s_waitcnt vmcnt(38)
; __device__ __forceinline__ float sigm(float x) { return __builtin_amdgcn_rcpf(1.f + __expf(-x)); }
; __device__ __forceinline__ void gemm_glu_merge(u16* __restrict__ proj, const u16* __restrict__ Wt) {
;     ...
;           u16* pr = proj + (size_t)row * 4096 + nt * 128 + wc * 32 + fr * 2;
;           const float s0 = acc[ai][0][m][0][j] * sigm(acc[ai][0][m][1][j]);
;           const float s1 = acc[ai][1][m][0][j] * sigm(acc[ai][1][m][1][j]);
;           const unsigned at = *(const unsigned*)pr, ga = *(const unsigned*)(pr + 2048), gs = *(const unsigned*)(pr + 3072);
;           const float m0 = sigm(__uint_as_float(ga << 16)) * __uint_as_float(at << 16) + sigm(__uint_as_float(gs << 16)) * s0;
;           const float m1 = sigm(__uint_as_float(ga & 0xffff0000u)) * __uint_as_float(at & 0xffff0000u) +
;                            sigm(__uint_as_float(gs & 0xffff0000u)) * s1;
;           __builtin_nontemporal_store(pack2(m0, m1), (unsigned*)pr);
.Lgw_join4:
	v_lshlrev_b32_e32 v238, 16, v162
	v_lshlrev_b32_e32 v239, 16, v163
	v_lshlrev_b32_e32 v240, 16, v164
	v_lshlrev_b32_e32 v241, 16, v165
	v_lshlrev_b32_e32 v242, 16, v166
	v_lshlrev_b32_e32 v243, 16, v167
	v_and_b32_e32 v162, 0xffff0000, v162
	v_and_b32_e32 v163, 0xffff0000, v163
	v_and_b32_e32 v164, 0xffff0000, v164
	v_and_b32_e32 v165, 0xffff0000, v165
	v_and_b32_e32 v166, 0xffff0000, v166
	v_and_b32_e32 v167, 0xffff0000, v167
	v_pk_mul_f32 v[240:241], v[240:241], s[30:31]
	v_pk_mul_f32 v[164:165], v[164:165], s[30:31]
	v_pk_mul_f32 v[242:243], v[242:243], s[30:31]
	v_pk_mul_f32 v[166:167], v[166:167], s[30:31]
	v_exp_f32_e32 v240, v240
	v_exp_f32_e32 v241, v241
	v_exp_f32_e32 v164, v164
	v_exp_f32_e32 v165, v165
	v_exp_f32_e32 v242, v242
	v_exp_f32_e32 v243, v243
	v_exp_f32_e32 v166, v166
	v_exp_f32_e32 v167, v167
	v_pk_add_f32 v[240:241], v[240:241], s[34:35]
	v_pk_add_f32 v[164:165], v[164:165], s[34:35]
	v_pk_add_f32 v[242:243], v[242:243], s[34:35]
	v_pk_add_f32 v[166:167], v[166:167], s[34:35]
	v_rcp_f32_e32 v240, v240
	v_rcp_f32_e32 v241, v241
	v_rcp_f32_e32 v164, v164
	v_rcp_f32_e32 v165, v165
	v_rcp_f32_e32 v242, v242
	v_rcp_f32_e32 v243, v243
	v_rcp_f32_e32 v166, v166
	v_rcp_f32_e32 v167, v167
	v_pk_mul_f32 v[238:239], v[240:241], v[238:239]
	v_pk_mul_f32 v[162:163], v[164:165], v[162:163]
	v_pk_fma_f32 v[238:239], v[242:243], v[80:81], v[238:239]
	v_pk_fma_f32 v[162:163], v[166:167], v[84:85], v[162:163]
	v_cvt_pk_bf16_f32 v240, v238, v162
	v_cvt_pk_bf16_f32 v241, v239, v163
	s_add_u32 s2, s64, 0x41000
	s_addc_u32 s3, s65, 0
	global_store_dword v137, v240, s[2:3] offset:-4096 nt
	s_add_u32 s2, s64, 0x43000
	s_addc_u32 s3, s65, 0
	global_store_dword v137, v241, s[2:3] offset:-4096 nt
	s_add_u32 s2, s64, 0x121000
	s_addc_u32 s3, s65, 0
	global_load_dword v198, v137, s[2:3] offset:-4096
	global_load_dword v200, v137, s[2:3]
	global_load_dword v202, v137, s[2:3] offset:2048
	s_add_u32 s2, s64, 0x123000
	s_addc_u32 s3, s65, 0
	global_load_dword v199, v137, s[2:3] offset:-4096
	global_load_dword v201, v137, s[2:3]
	global_load_dword v203, v137, s[2:3] offset:2048
	s_waitcnt vmcnt(40)
	v_lshlrev_b32_e32 v248, 16, v168
	v_lshlrev_b32_e32 v249, 16, v169
	v_lshlrev_b32_e32 v250, 16, v170
	v_lshlrev_b32_e32 v251, 16, v171
	v_lshlrev_b32_e32 v252, 16, v172
	v_lshlrev_b32_e32 v253, 16, v173
	v_and_b32_e32 v168, 0xffff0000, v168
	v_and_b32_e32 v169, 0xffff0000, v169
	v_and_b32_e32 v170, 0xffff0000, v170
	v_and_b32_e32 v171, 0xffff0000, v171
	v_and_b32_e32 v172, 0xffff0000, v172
	v_and_b32_e32 v173, 0xffff0000, v173
	v_pk_mul_f32 v[250:251], v[250:251], s[30:31]
	v_pk_mul_f32 v[170:171], v[170:171], s[30:31]
	v_pk_mul_f32 v[252:253], v[252:253], s[30:31]
	v_pk_mul_f32 v[172:173], v[172:173], s[30:31]
	v_exp_f32_e32 v250, v250
	v_exp_f32_e32 v251, v251
	v_exp_f32_e32 v170, v170
	v_exp_f32_e32 v171, v171
	v_exp_f32_e32 v252, v252
	v_exp_f32_e32 v253, v253
	v_exp_f32_e32 v172, v172
	v_exp_f32_e32 v173, v173
	v_pk_add_f32 v[250:251], v[250:251], s[34:35]
	v_pk_add_f32 v[170:171], v[170:171], s[34:35]
	v_pk_add_f32 v[252:253], v[252:253], s[34:35]
	v_pk_add_f32 v[172:173], v[172:173], s[34:35]
	v_rcp_f32_e32 v250, v250
	v_rcp_f32_e32 v251, v251
	v_rcp_f32_e32 v170, v170
	v_rcp_f32_e32 v171, v171
	v_rcp_f32_e32 v252, v252
	v_rcp_f32_e32 v253, v253
	v_rcp_f32_e32 v172, v172
	v_rcp_f32_e32 v173, v173
	v_pk_mul_f32 v[248:249], v[250:251], v[248:249]
	v_pk_mul_f32 v[168:169], v[170:171], v[168:169]
	v_pk_fma_f32 v[248:249], v[252:253], v[82:83], v[248:249]
	v_pk_fma_f32 v[168:169], v[172:173], v[86:87], v[168:169]
	v_cvt_pk_bf16_f32 v250, v248, v168
	v_cvt_pk_bf16_f32 v251, v249, v169
	s_add_u32 s2, s64, 0x45000
	s_addc_u32 s3, s65, 0
	global_store_dword v137, v250, s[2:3] offset:-4096 nt
	s_add_u32 s2, s64, 0x47000
	s_addc_u32 s3, s65, 0
	global_store_dword v137, v251, s[2:3] offset:-4096 nt
	s_add_u32 s2, s64, 0x125000
	s_addc_u32 s3, s65, 0
	global_load_dword v204, v137, s[2:3] offset:-4096
	global_load_dword v206, v137, s[2:3]
	global_load_dword v208, v137, s[2:3] offset:2048
	s_add_u32 s2, s64, 0x127000
	s_addc_u32 s3, s65, 0
	global_load_dword v205, v137, s[2:3] offset:-4096
	global_load_dword v207, v137, s[2:3]
	global_load_dword v209, v137, s[2:3] offset:2048
	v_pk_mul_f32 v[72:73], v[72:73], s[30:31]
	v_pk_mul_f32 v[76:77], v[76:77], s[30:31]
	v_pk_mul_f32 v[74:75], v[74:75], s[30:31]
	v_pk_mul_f32 v[78:79], v[78:79], s[30:31]
	v_exp_f32_e32 v72, v72
	v_exp_f32_e32 v73, v73
	v_exp_f32_e32 v76, v76
	v_exp_f32_e32 v77, v77
	v_exp_f32_e32 v74, v74
	v_exp_f32_e32 v75, v75
	v_exp_f32_e32 v78, v78
	v_exp_f32_e32 v79, v79
	v_pk_add_f32 v[72:73], v[72:73], s[34:35]
	v_pk_add_f32 v[76:77], v[76:77], s[34:35]
	v_pk_add_f32 v[74:75], v[74:75], s[34:35]
	v_pk_add_f32 v[78:79], v[78:79], s[34:35]
	v_rcp_f32_e32 v72, v72
	v_rcp_f32_e32 v73, v73
	v_rcp_f32_e32 v76, v76
	v_rcp_f32_e32 v77, v77
	v_rcp_f32_e32 v74, v74
	v_rcp_f32_e32 v75, v75
	v_rcp_f32_e32 v78, v78
	v_rcp_f32_e32 v79, v79
	v_pk_mul_f32 v[64:65], v[64:65], v[72:73]
	v_pk_mul_f32 v[68:69], v[68:69], v[76:77]
	v_pk_mul_f32 v[66:67], v[66:67], v[74:75]
	v_pk_mul_f32 v[70:71], v[70:71], v[78:79]
	s_waitcnt vmcnt(40)
; __device__ __forceinline__ float sigm(float x) { return __builtin_amdgcn_rcpf(1.f + __expf(-x)); }
; __device__ __forceinline__ void gemm_glu_merge(u16* __restrict__ proj, const u16* __restrict__ Wt) {
;     ...
;           u16* pr = proj + (size_t)row * 4096 + nt * 128 + wc * 32 + fr * 2;
;           const float s0 = acc[ai][0][m][0][j] * sigm(acc[ai][0][m][1][j]);
;           const float s1 = acc[ai][1][m][0][j] * sigm(acc[ai][1][m][1][j]);
;           const unsigned at = *(const unsigned*)pr, ga = *(const unsigned*)(pr + 2048), gs = *(const unsigned*)(pr + 3072);
;           const float m0 = sigm(__uint_as_float(ga << 16)) * __uint_as_float(at << 16) + sigm(__uint_as_float(gs << 16)) * s0;
;           const float m1 = sigm(__uint_as_float(ga & 0xffff0000u)) * __uint_as_float(at & 0xffff0000u) +
;                            sigm(__uint_as_float(gs & 0xffff0000u)) * s1;
;           __builtin_nontemporal_store(pack2(m0, m1), (unsigned*)pr);
	v_lshlrev_b32_e32 v238, 16, v174
	v_lshlrev_b32_e32 v239, 16, v175
	v_lshlrev_b32_e32 v240, 16, v176
	v_lshlrev_b32_e32 v241, 16, v177
	v_lshlrev_b32_e32 v242, 16, v178
	v_lshlrev_b32_e32 v243, 16, v179
	v_and_b32_e32 v174, 0xffff0000, v174
	v_and_b32_e32 v175, 0xffff0000, v175
	v_and_b32_e32 v176, 0xffff0000, v176
	v_and_b32_e32 v177, 0xffff0000, v177
	v_and_b32_e32 v178, 0xffff0000, v178
	v_and_b32_e32 v179, 0xffff0000, v179
	v_pk_mul_f32 v[240:241], v[240:241], s[30:31]
	v_pk_mul_f32 v[176:177], v[176:177], s[30:31]
	v_pk_mul_f32 v[242:243], v[242:243], s[30:31]
	v_pk_mul_f32 v[178:179], v[178:179], s[30:31]
	v_exp_f32_e32 v240, v240
	v_exp_f32_e32 v241, v241
	v_exp_f32_e32 v176, v176
	v_exp_f32_e32 v177, v177
	v_exp_f32_e32 v242, v242
	v_exp_f32_e32 v243, v243
	v_exp_f32_e32 v178, v178
	v_exp_f32_e32 v179, v179
	v_pk_add_f32 v[240:241], v[240:241], s[34:35]
	v_pk_add_f32 v[176:177], v[176:177], s[34:35]
	v_pk_add_f32 v[242:243], v[242:243], s[34:35]
	v_pk_add_f32 v[178:179], v[178:179], s[34:35]
	v_rcp_f32_e32 v240, v240
	v_rcp_f32_e32 v241, v241
	v_rcp_f32_e32 v176, v176
	v_rcp_f32_e32 v177, v177
	v_rcp_f32_e32 v242, v242
	v_rcp_f32_e32 v243, v243
	v_rcp_f32_e32 v178, v178
	v_rcp_f32_e32 v179, v179
	v_pk_mul_f32 v[238:239], v[240:241], v[238:239]
	v_pk_mul_f32 v[174:175], v[176:177], v[174:175]
	v_pk_fma_f32 v[238:239], v[242:243], v[64:65], v[238:239]
	v_pk_fma_f32 v[174:175], v[178:179], v[68:69], v[174:175]
	v_cvt_pk_bf16_f32 v240, v238, v174
	v_cvt_pk_bf16_f32 v241, v239, v175
	s_add_u32 s2, s64, 0x61000
	s_addc_u32 s3, s65, 0
	global_store_dword v137, v240, s[2:3] offset:-4096 nt
	s_add_u32 s2, s64, 0x63000
	s_addc_u32 s3, s65, 0
	global_store_dword v137, v241, s[2:3] offset:-4096 nt
	s_add_u32 s2, s64, 0x141000
	s_addc_u32 s3, s65, 0
	global_load_dword v210, v137, s[2:3] offset:-4096
	global_load_dword v212, v137, s[2:3]
	global_load_dword v214, v137, s[2:3] offset:2048
	s_add_u32 s2, s64, 0x143000
	s_addc_u32 s3, s65, 0
	global_load_dword v211, v137, s[2:3] offset:-4096
	global_load_dword v213, v137, s[2:3]
	global_load_dword v215, v137, s[2:3] offset:2048
	s_waitcnt vmcnt(40)
	v_lshlrev_b32_e32 v248, 16, v180
	v_lshlrev_b32_e32 v249, 16, v181
	v_lshlrev_b32_e32 v250, 16, v182
	v_lshlrev_b32_e32 v251, 16, v183
	v_lshlrev_b32_e32 v252, 16, v184
	v_lshlrev_b32_e32 v253, 16, v185
	v_and_b32_e32 v180, 0xffff0000, v180
	v_and_b32_e32 v181, 0xffff0000, v181
	v_and_b32_e32 v182, 0xffff0000, v182
	v_and_b32_e32 v183, 0xffff0000, v183
	v_and_b32_e32 v184, 0xffff0000, v184
	v_and_b32_e32 v185, 0xffff0000, v185
	v_pk_mul_f32 v[250:251], v[250:251], s[30:31]
	v_pk_mul_f32 v[182:183], v[182:183], s[30:31]
	v_pk_mul_f32 v[252:253], v[252:253], s[30:31]
	v_pk_mul_f32 v[184:185], v[184:185], s[30:31]
	v_exp_f32_e32 v250, v250
	v_exp_f32_e32 v251, v251
	v_exp_f32_e32 v182, v182
	v_exp_f32_e32 v183, v183
	v_exp_f32_e32 v252, v252
	v_exp_f32_e32 v253, v253
	v_exp_f32_e32 v184, v184
	v_exp_f32_e32 v185, v185
	v_pk_add_f32 v[250:251], v[250:251], s[34:35]
	v_pk_add_f32 v[182:183], v[182:183], s[34:35]
	v_pk_add_f32 v[252:253], v[252:253], s[34:35]
	v_pk_add_f32 v[184:185], v[184:185], s[34:35]
	v_rcp_f32_e32 v250, v250
	v_rcp_f32_e32 v251, v251
	v_rcp_f32_e32 v182, v182
	v_rcp_f32_e32 v183, v183
	v_rcp_f32_e32 v252, v252
	v_rcp_f32_e32 v253, v253
	v_rcp_f32_e32 v184, v184
	v_rcp_f32_e32 v185, v185
	v_pk_mul_f32 v[248:249], v[250:251], v[248:249]
	v_pk_mul_f32 v[180:181], v[182:183], v[180:181]
	v_pk_fma_f32 v[248:249], v[252:253], v[66:67], v[248:249]
	v_pk_fma_f32 v[180:181], v[184:185], v[70:71], v[180:181]
	v_cvt_pk_bf16_f32 v250, v248, v180
	v_cvt_pk_bf16_f32 v251, v249, v181
	s_add_u32 s2, s64, 0x65000
	s_addc_u32 s3, s65, 0
	global_store_dword v137, v250, s[2:3] offset:-4096 nt
	s_add_u32 s2, s64, 0x67000
	s_addc_u32 s3, s65, 0
	global_store_dword v137, v251, s[2:3] offset:-4096 nt
	s_add_u32 s2, s64, 0x145000
	s_addc_u32 s3, s65, 0
	global_load_dword v216, v137, s[2:3] offset:-4096
	global_load_dword v218, v137, s[2:3]
	global_load_dword v220, v137, s[2:3] offset:2048
	s_add_u32 s2, s64, 0x147000
	s_addc_u32 s3, s65, 0
	global_load_dword v217, v137, s[2:3] offset:-4096
	global_load_dword v219, v137, s[2:3]
	global_load_dword v221, v137, s[2:3] offset:2048
	v_pk_mul_f32 v[56:57], v[56:57], s[30:31]
	v_pk_mul_f32 v[60:61], v[60:61], s[30:31]
	v_pk_mul_f32 v[58:59], v[58:59], s[30:31]
	v_pk_mul_f32 v[62:63], v[62:63], s[30:31]
	v_exp_f32_e32 v56, v56
	v_exp_f32_e32 v57, v57
	v_exp_f32_e32 v60, v60
	v_exp_f32_e32 v61, v61
	v_exp_f32_e32 v58, v58
	v_exp_f32_e32 v59, v59
	v_exp_f32_e32 v62, v62
	v_exp_f32_e32 v63, v63
	v_pk_add_f32 v[56:57], v[56:57], s[34:35]
	v_pk_add_f32 v[60:61], v[60:61], s[34:35]
	v_pk_add_f32 v[58:59], v[58:59], s[34:35]
	v_pk_add_f32 v[62:63], v[62:63], s[34:35]
	v_rcp_f32_e32 v56, v56
	v_rcp_f32_e32 v57, v57
	v_rcp_f32_e32 v60, v60
	v_rcp_f32_e32 v61, v61
	v_rcp_f32_e32 v58, v58
	v_rcp_f32_e32 v59, v59
	v_rcp_f32_e32 v62, v62
	v_rcp_f32_e32 v63, v63
	v_pk_mul_f32 v[48:49], v[48:49], v[56:57]
	v_pk_mul_f32 v[52:53], v[52:53], v[60:61]
	v_pk_mul_f32 v[50:51], v[50:51], v[58:59]
	v_pk_mul_f32 v[54:55], v[54:55], v[62:63]
	s_waitcnt vmcnt(40)
; __device__ __forceinline__ float sigm(float x) { return __builtin_amdgcn_rcpf(1.f + __expf(-x)); }
; __device__ __forceinline__ void gemm_glu_merge(u16* __restrict__ proj, const u16* __restrict__ Wt) {
;     ...
;           u16* pr = proj + (size_t)row * 4096 + nt * 128 + wc * 32 + fr * 2;
;           const float s0 = acc[ai][0][m][0][j] * sigm(acc[ai][0][m][1][j]);
;           const float s1 = acc[ai][1][m][0][j] * sigm(acc[ai][1][m][1][j]);
;           const unsigned at = *(const unsigned*)pr, ga = *(const unsigned*)(pr + 2048), gs = *(const unsigned*)(pr + 3072);
;           const float m0 = sigm(__uint_as_float(ga << 16)) * __uint_as_float(at << 16) + sigm(__uint_as_float(gs << 16)) * s0;
;           const float m1 = sigm(__uint_as_float(ga & 0xffff0000u)) * __uint_as_float(at & 0xffff0000u) +
;                            sigm(__uint_as_float(gs & 0xffff0000u)) * s1;
;           __builtin_nontemporal_store(pack2(m0, m1), (unsigned*)pr);
	v_lshlrev_b32_e32 v238, 16, v186
	v_lshlrev_b32_e32 v239, 16, v187
	v_lshlrev_b32_e32 v240, 16, v188
	v_lshlrev_b32_e32 v241, 16, v189
	v_lshlrev_b32_e32 v242, 16, v190
	v_lshlrev_b32_e32 v243, 16, v191
	v_and_b32_e32 v186, 0xffff0000, v186
	v_and_b32_e32 v187, 0xffff0000, v187
	v_and_b32_e32 v188, 0xffff0000, v188
	v_and_b32_e32 v189, 0xffff0000, v189
	v_and_b32_e32 v190, 0xffff0000, v190
	v_and_b32_e32 v191, 0xffff0000, v191
	v_pk_mul_f32 v[240:241], v[240:241], s[30:31]
	v_pk_mul_f32 v[188:189], v[188:189], s[30:31]
	v_pk_mul_f32 v[242:243], v[242:243], s[30:31]
	v_pk_mul_f32 v[190:191], v[190:191], s[30:31]
	v_exp_f32_e32 v240, v240
	v_exp_f32_e32 v241, v241
	v_exp_f32_e32 v188, v188
	v_exp_f32_e32 v189, v189
	v_exp_f32_e32 v242, v242
	v_exp_f32_e32 v243, v243
	v_exp_f32_e32 v190, v190
	v_exp_f32_e32 v191, v191
	v_pk_add_f32 v[240:241], v[240:241], s[34:35]
	v_pk_add_f32 v[188:189], v[188:189], s[34:35]
	v_pk_add_f32 v[242:243], v[242:243], s[34:35]
	v_pk_add_f32 v[190:191], v[190:191], s[34:35]
	v_rcp_f32_e32 v240, v240
	v_rcp_f32_e32 v241, v241
	v_rcp_f32_e32 v188, v188
	v_rcp_f32_e32 v189, v189
	v_rcp_f32_e32 v242, v242
	v_rcp_f32_e32 v243, v243
	v_rcp_f32_e32 v190, v190
	v_rcp_f32_e32 v191, v191
	v_pk_mul_f32 v[238:239], v[240:241], v[238:239]
	v_pk_mul_f32 v[186:187], v[188:189], v[186:187]
	v_pk_fma_f32 v[238:239], v[242:243], v[48:49], v[238:239]
	v_pk_fma_f32 v[186:187], v[190:191], v[52:53], v[186:187]
	v_cvt_pk_bf16_f32 v240, v238, v186
	v_cvt_pk_bf16_f32 v241, v239, v187
	s_add_u32 s2, s64, 0x101000
	s_addc_u32 s3, s65, 0
	global_store_dword v137, v240, s[2:3] offset:-4096 nt
	s_add_u32 s2, s64, 0x103000
	s_addc_u32 s3, s65, 0
	global_store_dword v137, v241, s[2:3] offset:-4096 nt
	s_add_u32 s2, s64, 0x161000
	s_addc_u32 s3, s65, 0
	global_load_dword v222, v137, s[2:3] offset:-4096
	global_load_dword v224, v137, s[2:3]
	global_load_dword v226, v137, s[2:3] offset:2048
	s_add_u32 s2, s64, 0x163000
	s_addc_u32 s3, s65, 0
	global_load_dword v223, v137, s[2:3] offset:-4096
	global_load_dword v225, v137, s[2:3]
	global_load_dword v227, v137, s[2:3] offset:2048
	s_waitcnt vmcnt(40)
	v_lshlrev_b32_e32 v248, 16, v192
	v_lshlrev_b32_e32 v249, 16, v193
	v_lshlrev_b32_e32 v250, 16, v194
	v_lshlrev_b32_e32 v251, 16, v195
	v_lshlrev_b32_e32 v252, 16, v196
	v_lshlrev_b32_e32 v253, 16, v197
	v_and_b32_e32 v192, 0xffff0000, v192
	v_and_b32_e32 v193, 0xffff0000, v193
	v_and_b32_e32 v194, 0xffff0000, v194
	v_and_b32_e32 v195, 0xffff0000, v195
	v_and_b32_e32 v196, 0xffff0000, v196
	v_and_b32_e32 v197, 0xffff0000, v197
	v_pk_mul_f32 v[250:251], v[250:251], s[30:31]
	v_pk_mul_f32 v[194:195], v[194:195], s[30:31]
	v_pk_mul_f32 v[252:253], v[252:253], s[30:31]
	v_pk_mul_f32 v[196:197], v[196:197], s[30:31]
	v_exp_f32_e32 v250, v250
	v_exp_f32_e32 v251, v251
	v_exp_f32_e32 v194, v194
	v_exp_f32_e32 v195, v195
	v_exp_f32_e32 v252, v252
	v_exp_f32_e32 v253, v253
	v_exp_f32_e32 v196, v196
	v_exp_f32_e32 v197, v197
	v_pk_add_f32 v[250:251], v[250:251], s[34:35]
	v_pk_add_f32 v[194:195], v[194:195], s[34:35]
	v_pk_add_f32 v[252:253], v[252:253], s[34:35]
	v_pk_add_f32 v[196:197], v[196:197], s[34:35]
	v_rcp_f32_e32 v250, v250
	v_rcp_f32_e32 v251, v251
	v_rcp_f32_e32 v194, v194
	v_rcp_f32_e32 v195, v195
	v_rcp_f32_e32 v252, v252
	v_rcp_f32_e32 v253, v253
	v_rcp_f32_e32 v196, v196
	v_rcp_f32_e32 v197, v197
	v_pk_mul_f32 v[248:249], v[250:251], v[248:249]
	v_pk_mul_f32 v[192:193], v[194:195], v[192:193]
	v_pk_fma_f32 v[248:249], v[252:253], v[50:51], v[248:249]
	v_pk_fma_f32 v[192:193], v[196:197], v[54:55], v[192:193]
	v_cvt_pk_bf16_f32 v250, v248, v192
	v_cvt_pk_bf16_f32 v251, v249, v193
	s_add_u32 s2, s64, 0x105000
	s_addc_u32 s3, s65, 0
	global_store_dword v137, v250, s[2:3] offset:-4096 nt
	s_add_u32 s2, s64, 0x107000
	s_addc_u32 s3, s65, 0
	global_store_dword v137, v251, s[2:3] offset:-4096 nt
	s_add_u32 s2, s64, 0x165000
	s_addc_u32 s3, s65, 0
	global_load_dword v228, v137, s[2:3] offset:-4096
	global_load_dword v230, v137, s[2:3]
	global_load_dword v232, v137, s[2:3] offset:2048
	s_add_u32 s2, s64, 0x167000
	s_addc_u32 s3, s65, 0
	global_load_dword v229, v137, s[2:3] offset:-4096
	global_load_dword v231, v137, s[2:3]
	global_load_dword v233, v137, s[2:3] offset:2048
	v_pk_mul_f32 v[40:41], v[40:41], s[30:31]
	v_pk_mul_f32 v[44:45], v[44:45], s[30:31]
	v_pk_mul_f32 v[42:43], v[42:43], s[30:31]
	v_pk_mul_f32 v[46:47], v[46:47], s[30:31]
	v_exp_f32_e32 v40, v40
	v_exp_f32_e32 v41, v41
	v_exp_f32_e32 v44, v44
	v_exp_f32_e32 v45, v45
	v_exp_f32_e32 v42, v42
	v_exp_f32_e32 v43, v43
	v_exp_f32_e32 v46, v46
	v_exp_f32_e32 v47, v47
	v_pk_add_f32 v[40:41], v[40:41], s[34:35]
	v_pk_add_f32 v[44:45], v[44:45], s[34:35]
	v_pk_add_f32 v[42:43], v[42:43], s[34:35]
	v_pk_add_f32 v[46:47], v[46:47], s[34:35]
	v_rcp_f32_e32 v40, v40
	v_rcp_f32_e32 v41, v41
	v_rcp_f32_e32 v44, v44
	v_rcp_f32_e32 v45, v45
	v_rcp_f32_e32 v42, v42
	v_rcp_f32_e32 v43, v43
	v_rcp_f32_e32 v46, v46
	v_rcp_f32_e32 v47, v47
	v_pk_mul_f32 v[32:33], v[32:33], v[40:41]
	v_pk_mul_f32 v[36:37], v[36:37], v[44:45]
	v_pk_mul_f32 v[34:35], v[34:35], v[42:43]
	v_pk_mul_f32 v[38:39], v[38:39], v[46:47]
	s_waitcnt vmcnt(40)
; __device__ __forceinline__ float sigm(float x) { return __builtin_amdgcn_rcpf(1.f + __expf(-x)); }
; __device__ __forceinline__ void gemm_glu_merge(u16* __restrict__ proj, const u16* __restrict__ Wt) {
;     ...
;           u16* pr = proj + (size_t)row * 4096 + nt * 128 + wc * 32 + fr * 2;
;           const float s0 = acc[ai][0][m][0][j] * sigm(acc[ai][0][m][1][j]);
;           const float s1 = acc[ai][1][m][0][j] * sigm(acc[ai][1][m][1][j]);
;           const unsigned at = *(const unsigned*)pr, ga = *(const unsigned*)(pr + 2048), gs = *(const unsigned*)(pr + 3072);
;           const float m0 = sigm(__uint_as_float(ga << 16)) * __uint_as_float(at << 16) + sigm(__uint_as_float(gs << 16)) * s0;
;           const float m1 = sigm(__uint_as_float(ga & 0xffff0000u)) * __uint_as_float(at & 0xffff0000u) +
;                            sigm(__uint_as_float(gs & 0xffff0000u)) * s1;
;           __builtin_nontemporal_store(pack2(m0, m1), (unsigned*)pr);
	v_lshlrev_b32_e32 v238, 16, v198
	v_lshlrev_b32_e32 v239, 16, v199
	v_lshlrev_b32_e32 v240, 16, v200
	v_lshlrev_b32_e32 v241, 16, v201
	v_lshlrev_b32_e32 v242, 16, v202
	v_lshlrev_b32_e32 v243, 16, v203
	v_and_b32_e32 v198, 0xffff0000, v198
	v_and_b32_e32 v199, 0xffff0000, v199
	v_and_b32_e32 v200, 0xffff0000, v200
	v_and_b32_e32 v201, 0xffff0000, v201
	v_and_b32_e32 v202, 0xffff0000, v202
	v_and_b32_e32 v203, 0xffff0000, v203
	v_pk_mul_f32 v[240:241], v[240:241], s[30:31]
	v_pk_mul_f32 v[200:201], v[200:201], s[30:31]
	v_pk_mul_f32 v[242:243], v[242:243], s[30:31]
	v_pk_mul_f32 v[202:203], v[202:203], s[30:31]
	v_exp_f32_e32 v240, v240
	v_exp_f32_e32 v241, v241
	v_exp_f32_e32 v200, v200
	v_exp_f32_e32 v201, v201
	v_exp_f32_e32 v242, v242
	v_exp_f32_e32 v243, v243
	v_exp_f32_e32 v202, v202
	v_exp_f32_e32 v203, v203
	v_pk_add_f32 v[240:241], v[240:241], s[34:35]
	v_pk_add_f32 v[200:201], v[200:201], s[34:35]
	v_pk_add_f32 v[242:243], v[242:243], s[34:35]
	v_pk_add_f32 v[202:203], v[202:203], s[34:35]
	v_rcp_f32_e32 v240, v240
	v_rcp_f32_e32 v241, v241
	v_rcp_f32_e32 v200, v200
	v_rcp_f32_e32 v201, v201
	v_rcp_f32_e32 v242, v242
	v_rcp_f32_e32 v243, v243
	v_rcp_f32_e32 v202, v202
	v_rcp_f32_e32 v203, v203
	v_pk_mul_f32 v[238:239], v[240:241], v[238:239]
	v_pk_mul_f32 v[198:199], v[200:201], v[198:199]
	v_pk_fma_f32 v[238:239], v[242:243], v[32:33], v[238:239]
	v_pk_fma_f32 v[198:199], v[202:203], v[36:37], v[198:199]
	v_cvt_pk_bf16_f32 v240, v238, v198
	v_cvt_pk_bf16_f32 v241, v239, v199
	s_add_u32 s2, s64, 0x121000
	s_addc_u32 s3, s65, 0
	global_store_dword v137, v240, s[2:3] offset:-4096 nt
	s_add_u32 s2, s64, 0x123000
	s_addc_u32 s3, s65, 0
	global_store_dword v137, v241, s[2:3] offset:-4096 nt
	s_waitcnt vmcnt(34)
	v_lshlrev_b32_e32 v248, 16, v204
	v_lshlrev_b32_e32 v249, 16, v205
	v_lshlrev_b32_e32 v250, 16, v206
	v_lshlrev_b32_e32 v251, 16, v207
	v_lshlrev_b32_e32 v252, 16, v208
	v_lshlrev_b32_e32 v253, 16, v209
	v_and_b32_e32 v204, 0xffff0000, v204
	v_and_b32_e32 v205, 0xffff0000, v205
	v_and_b32_e32 v206, 0xffff0000, v206
	v_and_b32_e32 v207, 0xffff0000, v207
	v_and_b32_e32 v208, 0xffff0000, v208
	v_and_b32_e32 v209, 0xffff0000, v209
	v_pk_mul_f32 v[250:251], v[250:251], s[30:31]
	v_pk_mul_f32 v[206:207], v[206:207], s[30:31]
	v_pk_mul_f32 v[252:253], v[252:253], s[30:31]
	v_pk_mul_f32 v[208:209], v[208:209], s[30:31]
	v_exp_f32_e32 v250, v250
	v_exp_f32_e32 v251, v251
	v_exp_f32_e32 v206, v206
	v_exp_f32_e32 v207, v207
	v_exp_f32_e32 v252, v252
	v_exp_f32_e32 v253, v253
	v_exp_f32_e32 v208, v208
	v_exp_f32_e32 v209, v209
	v_pk_add_f32 v[250:251], v[250:251], s[34:35]
	v_pk_add_f32 v[206:207], v[206:207], s[34:35]
	v_pk_add_f32 v[252:253], v[252:253], s[34:35]
	v_pk_add_f32 v[208:209], v[208:209], s[34:35]
	v_rcp_f32_e32 v250, v250
	v_rcp_f32_e32 v251, v251
	v_rcp_f32_e32 v206, v206
	v_rcp_f32_e32 v207, v207
	v_rcp_f32_e32 v252, v252
	v_rcp_f32_e32 v253, v253
	v_rcp_f32_e32 v208, v208
	v_rcp_f32_e32 v209, v209
	v_pk_mul_f32 v[248:249], v[250:251], v[248:249]
	v_pk_mul_f32 v[204:205], v[206:207], v[204:205]
	v_pk_fma_f32 v[248:249], v[252:253], v[34:35], v[248:249]
	v_pk_fma_f32 v[204:205], v[208:209], v[38:39], v[204:205]
	v_cvt_pk_bf16_f32 v250, v248, v204
	v_cvt_pk_bf16_f32 v251, v249, v205
	s_add_u32 s2, s64, 0x125000
	s_addc_u32 s3, s65, 0
	global_store_dword v137, v250, s[2:3] offset:-4096 nt
	s_add_u32 s2, s64, 0x127000
	s_addc_u32 s3, s65, 0
	global_store_dword v137, v251, s[2:3] offset:-4096 nt
	v_pk_mul_f32 v[24:25], v[24:25], s[30:31]
	v_pk_mul_f32 v[28:29], v[28:29], s[30:31]
	v_pk_mul_f32 v[26:27], v[26:27], s[30:31]
	v_pk_mul_f32 v[30:31], v[30:31], s[30:31]
	v_exp_f32_e32 v24, v24
	v_exp_f32_e32 v25, v25
	v_exp_f32_e32 v28, v28
	v_exp_f32_e32 v29, v29
	v_exp_f32_e32 v26, v26
	v_exp_f32_e32 v27, v27
	v_exp_f32_e32 v30, v30
	v_exp_f32_e32 v31, v31
	v_pk_add_f32 v[24:25], v[24:25], s[34:35]
	v_pk_add_f32 v[28:29], v[28:29], s[34:35]
	v_pk_add_f32 v[26:27], v[26:27], s[34:35]
	v_pk_add_f32 v[30:31], v[30:31], s[34:35]
	v_rcp_f32_e32 v24, v24
	v_rcp_f32_e32 v25, v25
	v_rcp_f32_e32 v28, v28
	v_rcp_f32_e32 v29, v29
	v_rcp_f32_e32 v26, v26
	v_rcp_f32_e32 v27, v27
	v_rcp_f32_e32 v30, v30
	v_rcp_f32_e32 v31, v31
	v_pk_mul_f32 v[16:17], v[16:17], v[24:25]
	v_pk_mul_f32 v[20:21], v[20:21], v[28:29]
	v_pk_mul_f32 v[18:19], v[18:19], v[26:27]
	v_pk_mul_f32 v[22:23], v[22:23], v[30:31]
	s_waitcnt vmcnt(28)
	v_lshlrev_b32_e32 v238, 16, v210
	v_lshlrev_b32_e32 v239, 16, v211
	v_lshlrev_b32_e32 v240, 16, v212
	v_lshlrev_b32_e32 v241, 16, v213
	v_lshlrev_b32_e32 v242, 16, v214
	v_lshlrev_b32_e32 v243, 16, v215
	v_and_b32_e32 v210, 0xffff0000, v210
	v_and_b32_e32 v211, 0xffff0000, v211
	v_and_b32_e32 v212, 0xffff0000, v212
	v_and_b32_e32 v213, 0xffff0000, v213
	v_and_b32_e32 v214, 0xffff0000, v214
	v_and_b32_e32 v215, 0xffff0000, v215
	v_pk_mul_f32 v[240:241], v[240:241], s[30:31]
	v_pk_mul_f32 v[212:213], v[212:213], s[30:31]
	v_pk_mul_f32 v[242:243], v[242:243], s[30:31]
	v_pk_mul_f32 v[214:215], v[214:215], s[30:31]
	v_exp_f32_e32 v240, v240
	v_exp_f32_e32 v241, v241
	v_exp_f32_e32 v212, v212
	v_exp_f32_e32 v213, v213
	v_exp_f32_e32 v242, v242
	v_exp_f32_e32 v243, v243
	v_exp_f32_e32 v214, v214
	v_exp_f32_e32 v215, v215
	v_pk_add_f32 v[240:241], v[240:241], s[34:35]
	v_pk_add_f32 v[212:213], v[212:213], s[34:35]
	v_pk_add_f32 v[242:243], v[242:243], s[34:35]
	v_pk_add_f32 v[214:215], v[214:215], s[34:35]
	v_rcp_f32_e32 v240, v240
	v_rcp_f32_e32 v241, v241
	v_rcp_f32_e32 v212, v212
	v_rcp_f32_e32 v213, v213
	v_rcp_f32_e32 v242, v242
	v_rcp_f32_e32 v243, v243
	v_rcp_f32_e32 v214, v214
	v_rcp_f32_e32 v215, v215
	v_pk_mul_f32 v[238:239], v[240:241], v[238:239]
	v_pk_mul_f32 v[210:211], v[212:213], v[210:211]
	v_pk_fma_f32 v[238:239], v[242:243], v[16:17], v[238:239]
	v_pk_fma_f32 v[210:211], v[214:215], v[20:21], v[210:211]
	v_cvt_pk_bf16_f32 v240, v238, v210
	v_cvt_pk_bf16_f32 v241, v239, v211
	s_add_u32 s2, s64, 0x141000
	s_addc_u32 s3, s65, 0
	global_store_dword v137, v240, s[2:3] offset:-4096 nt
	s_add_u32 s2, s64, 0x143000
	s_addc_u32 s3, s65, 0
	global_store_dword v137, v241, s[2:3] offset:-4096 nt
	s_waitcnt vmcnt(22)
; __device__ __forceinline__ float sigm(float x) { return __builtin_amdgcn_rcpf(1.f + __expf(-x)); }
; __device__ __forceinline__ void gemm_glu_merge(u16* __restrict__ proj, const u16* __restrict__ Wt) {
;     ...
;   for (int nt = 0; nt < 8; ++nt) {
;     ...
;           u16* pr = proj + (size_t)row * 4096 + nt * 128 + wc * 32 + fr * 2;
;           const float s0 = acc[ai][0][m][0][j] * sigm(acc[ai][0][m][1][j]);
;           const float s1 = acc[ai][1][m][0][j] * sigm(acc[ai][1][m][1][j]);
;           const unsigned at = *(const unsigned*)pr, ga = *(const unsigned*)(pr + 2048), gs = *(const unsigned*)(pr + 3072);
;           const float m0 = sigm(__uint_as_float(ga << 16)) * __uint_as_float(at << 16) + sigm(__uint_as_float(gs << 16)) * s0;
;           const float m1 = sigm(__uint_as_float(ga & 0xffff0000u)) * __uint_as_float(at & 0xffff0000u) +
;                            sigm(__uint_as_float(gs & 0xffff0000u)) * s1;
;           __builtin_nontemporal_store(pack2(m0, m1), (unsigned*)pr);
	v_lshlrev_b32_e32 v248, 16, v216
	v_lshlrev_b32_e32 v249, 16, v217
	v_lshlrev_b32_e32 v250, 16, v218
	v_lshlrev_b32_e32 v251, 16, v219
	v_lshlrev_b32_e32 v252, 16, v220
	v_lshlrev_b32_e32 v253, 16, v221
	v_and_b32_e32 v216, 0xffff0000, v216
	v_and_b32_e32 v217, 0xffff0000, v217
	v_and_b32_e32 v218, 0xffff0000, v218
	v_and_b32_e32 v219, 0xffff0000, v219
	v_and_b32_e32 v220, 0xffff0000, v220
	v_and_b32_e32 v221, 0xffff0000, v221
	v_pk_mul_f32 v[250:251], v[250:251], s[30:31]
	v_pk_mul_f32 v[218:219], v[218:219], s[30:31]
	v_pk_mul_f32 v[252:253], v[252:253], s[30:31]
	v_pk_mul_f32 v[220:221], v[220:221], s[30:31]
	v_exp_f32_e32 v250, v250
	v_exp_f32_e32 v251, v251
	v_exp_f32_e32 v218, v218
	v_exp_f32_e32 v219, v219
	v_exp_f32_e32 v252, v252
	v_exp_f32_e32 v253, v253
	v_exp_f32_e32 v220, v220
	v_exp_f32_e32 v221, v221
	v_pk_add_f32 v[250:251], v[250:251], s[34:35]
	v_pk_add_f32 v[218:219], v[218:219], s[34:35]
	v_pk_add_f32 v[252:253], v[252:253], s[34:35]
	v_pk_add_f32 v[220:221], v[220:221], s[34:35]
	v_rcp_f32_e32 v250, v250
	v_rcp_f32_e32 v251, v251
	v_rcp_f32_e32 v218, v218
	v_rcp_f32_e32 v219, v219
	v_rcp_f32_e32 v252, v252
	v_rcp_f32_e32 v253, v253
	v_rcp_f32_e32 v220, v220
	v_rcp_f32_e32 v221, v221
	v_pk_mul_f32 v[248:249], v[250:251], v[248:249]
	v_pk_mul_f32 v[216:217], v[218:219], v[216:217]
	v_pk_fma_f32 v[248:249], v[252:253], v[18:19], v[248:249]
	v_pk_fma_f32 v[216:217], v[220:221], v[22:23], v[216:217]
	v_cvt_pk_bf16_f32 v250, v248, v216
	v_cvt_pk_bf16_f32 v251, v249, v217
	s_add_u32 s2, s64, 0x145000
	s_addc_u32 s3, s65, 0
	global_store_dword v137, v250, s[2:3] offset:-4096 nt
	s_add_u32 s2, s64, 0x147000
	s_addc_u32 s3, s65, 0
	global_store_dword v137, v251, s[2:3] offset:-4096 nt
	v_pk_mul_f32 v[8:9], v[8:9], s[30:31]
	v_pk_mul_f32 v[12:13], v[12:13], s[30:31]
	v_pk_mul_f32 v[10:11], v[10:11], s[30:31]
	v_pk_mul_f32 v[14:15], v[14:15], s[30:31]
	v_exp_f32_e32 v8, v8
	v_exp_f32_e32 v9, v9
	v_exp_f32_e32 v12, v12
	v_exp_f32_e32 v13, v13
	v_exp_f32_e32 v10, v10
	v_exp_f32_e32 v11, v11
	v_exp_f32_e32 v14, v14
	v_exp_f32_e32 v15, v15
	v_pk_add_f32 v[8:9], v[8:9], s[34:35]
	v_pk_add_f32 v[12:13], v[12:13], s[34:35]
	v_pk_add_f32 v[10:11], v[10:11], s[34:35]
	v_pk_add_f32 v[14:15], v[14:15], s[34:35]
	v_rcp_f32_e32 v8, v8
	v_rcp_f32_e32 v9, v9
	v_rcp_f32_e32 v12, v12
	v_rcp_f32_e32 v13, v13
	v_rcp_f32_e32 v10, v10
	v_rcp_f32_e32 v11, v11
	v_rcp_f32_e32 v14, v14
	v_rcp_f32_e32 v15, v15
	v_pk_mul_f32 v[0:1], v[0:1], v[8:9]
	v_pk_mul_f32 v[4:5], v[4:5], v[12:13]
	v_pk_mul_f32 v[2:3], v[2:3], v[10:11]
	v_pk_mul_f32 v[6:7], v[6:7], v[14:15]
	s_waitcnt vmcnt(16)
	v_lshlrev_b32_e32 v238, 16, v222
	v_lshlrev_b32_e32 v239, 16, v223
	v_lshlrev_b32_e32 v240, 16, v224
	v_lshlrev_b32_e32 v241, 16, v225
	v_lshlrev_b32_e32 v242, 16, v226
	v_lshlrev_b32_e32 v243, 16, v227
	v_and_b32_e32 v222, 0xffff0000, v222
	v_and_b32_e32 v223, 0xffff0000, v223
	v_and_b32_e32 v224, 0xffff0000, v224
	v_and_b32_e32 v225, 0xffff0000, v225
	v_and_b32_e32 v226, 0xffff0000, v226
	v_and_b32_e32 v227, 0xffff0000, v227
	v_pk_mul_f32 v[240:241], v[240:241], s[30:31]
	v_pk_mul_f32 v[224:225], v[224:225], s[30:31]
	v_pk_mul_f32 v[242:243], v[242:243], s[30:31]
	v_pk_mul_f32 v[226:227], v[226:227], s[30:31]
	v_exp_f32_e32 v240, v240
	v_exp_f32_e32 v241, v241
	v_exp_f32_e32 v224, v224
	v_exp_f32_e32 v225, v225
	v_exp_f32_e32 v242, v242
	v_exp_f32_e32 v243, v243
	v_exp_f32_e32 v226, v226
	v_exp_f32_e32 v227, v227
	v_pk_add_f32 v[240:241], v[240:241], s[34:35]
	v_pk_add_f32 v[224:225], v[224:225], s[34:35]
	v_pk_add_f32 v[242:243], v[242:243], s[34:35]
	v_pk_add_f32 v[226:227], v[226:227], s[34:35]
	v_rcp_f32_e32 v240, v240
	v_rcp_f32_e32 v241, v241
	v_rcp_f32_e32 v224, v224
	v_rcp_f32_e32 v225, v225
	v_rcp_f32_e32 v242, v242
	v_rcp_f32_e32 v243, v243
	v_rcp_f32_e32 v226, v226
	v_rcp_f32_e32 v227, v227
	v_pk_mul_f32 v[238:239], v[240:241], v[238:239]
	v_pk_mul_f32 v[222:223], v[224:225], v[222:223]
	v_pk_fma_f32 v[238:239], v[242:243], v[0:1], v[238:239]
	v_pk_fma_f32 v[222:223], v[226:227], v[4:5], v[222:223]
	v_cvt_pk_bf16_f32 v240, v238, v222
	v_cvt_pk_bf16_f32 v241, v239, v223
	s_add_u32 s2, s64, 0x161000
	s_addc_u32 s3, s65, 0
	global_store_dword v137, v240, s[2:3] offset:-4096 nt
	s_add_u32 s2, s64, 0x163000
	s_addc_u32 s3, s65, 0
	global_store_dword v137, v241, s[2:3] offset:-4096 nt
	s_waitcnt vmcnt(10)
	v_lshlrev_b32_e32 v248, 16, v228
	v_lshlrev_b32_e32 v249, 16, v229
	v_lshlrev_b32_e32 v250, 16, v230
	v_lshlrev_b32_e32 v251, 16, v231
	v_lshlrev_b32_e32 v252, 16, v232
	v_lshlrev_b32_e32 v253, 16, v233
	v_and_b32_e32 v228, 0xffff0000, v228
	v_and_b32_e32 v229, 0xffff0000, v229
	v_and_b32_e32 v230, 0xffff0000, v230
	v_and_b32_e32 v231, 0xffff0000, v231
	v_and_b32_e32 v232, 0xffff0000, v232
	v_and_b32_e32 v233, 0xffff0000, v233
	v_pk_mul_f32 v[250:251], v[250:251], s[30:31]
	v_pk_mul_f32 v[230:231], v[230:231], s[30:31]
	v_pk_mul_f32 v[252:253], v[252:253], s[30:31]
	v_pk_mul_f32 v[232:233], v[232:233], s[30:31]
	v_exp_f32_e32 v250, v250
	v_exp_f32_e32 v251, v251
	v_exp_f32_e32 v230, v230
	v_exp_f32_e32 v231, v231
	v_exp_f32_e32 v252, v252
	v_exp_f32_e32 v253, v253
	v_exp_f32_e32 v232, v232
	v_exp_f32_e32 v233, v233
	v_pk_add_f32 v[250:251], v[250:251], s[34:35]
	v_pk_add_f32 v[230:231], v[230:231], s[34:35]
	v_pk_add_f32 v[252:253], v[252:253], s[34:35]
	v_pk_add_f32 v[232:233], v[232:233], s[34:35]
	v_rcp_f32_e32 v250, v250
	v_rcp_f32_e32 v251, v251
	v_rcp_f32_e32 v230, v230
	v_rcp_f32_e32 v231, v231
	v_rcp_f32_e32 v252, v252
	v_rcp_f32_e32 v253, v253
	v_rcp_f32_e32 v232, v232
	v_rcp_f32_e32 v233, v233
	v_pk_mul_f32 v[248:249], v[250:251], v[248:249]
	v_pk_mul_f32 v[228:229], v[230:231], v[228:229]
	v_pk_fma_f32 v[248:249], v[252:253], v[2:3], v[248:249]
	v_pk_fma_f32 v[228:229], v[232:233], v[6:7], v[228:229]
	v_cvt_pk_bf16_f32 v250, v248, v228
	v_cvt_pk_bf16_f32 v251, v249, v229
	s_add_u32 s2, s64, 0x165000
	s_addc_u32 s3, s65, 0
	global_store_dword v137, v250, s[2:3] offset:-4096 nt
	s_add_u32 s2, s64, 0x167000
	s_addc_u32 s3, s65, 0
	global_store_dword v137, v251, s[2:3] offset:-4096 nt
	s_mov_b32 s30, 0x80100
	s_mov_b32 s31, 0x20100
	s_mov_b32 s34, 0x30100
	s_mov_b32 s35, 0x100100
	s_add_i32 s12, s12, 1
	s_cmp_lg_u32 s12, 8
	s_cbranch_scc0 .LBB0_367
